# c12 + phase-3 forget-weight table slices held in 128 VGPRs for the whole row loop (no per-row LDS re-reads)
# baseline (speedup 1.0000x reference)
; DEVI int ltid(int wv) { int t = (wv << 6) | (int)__builtin_amdgcn_mbcnt_hi(~0u, __builtin_amdgcn_mbcnt_lo(~0u, 0u)); asm volatile("" : "+v"(t)); return t; }
; DEVI int lbid() { int t = blockIdx.x; asm volatile("" : "+s"(t)); return t; }
; DEVI int lgrid() { int t = gridDim.x; asm volatile("" : "+s"(t)); return t; }
; DEVI void norm_phase(const float* __restrict__ x, const float* __restrict__ gain, bf16_t* __restrict__ out,
;                      const float* wf_src, const float* bf_src, float* logf, char* lds, int wv) {
;     const int tid = ltid(wv), lane = tid & 63, wave = tid >> 6;
;     float* wf = (float*)lds;
;     if (wf_src) {
;         for (int e = tid; e < 8192; e += 512) { const int k = e >> 3, h = e & 7; wf[h * 1024 + k] = wf_src[(size_t)k * NIN + 3072 + h]; }
;         __syncthreads();
;     }
;     f32x4 g[4];
; #pragma unroll
;     for (int j = 0; j < 4; ++j) g[j] = *(const f32x4*)(gain + j * 256 + lane * 4);
;     const int nw = lgrid() * 8;
;     for (int row0 = lbid() * 8 + wave; row0 < T_TOK; row0 += 2 * nw) {
;     ...
;                     for (int j = 0; j < 4; ++j) { const f32x4 w = *(const f32x4*)(wf + h * 1024 + j * 256 + lane * 4); d += v[q][j][0] * w[0] + v[q][j][1] * w[1] + v[q][j][2] * w[2] + v[q][j][3] * w[3]; }
.LBB0_476:
	s_load_dwordx2 s[8:9], s[0:1], 0xd8
	v_ashrrev_i32_e32 v0, 6, v2
	s_waitcnt lgkmcnt(0)
	s_mov_b32 s9, s2
	s_waitcnt vmcnt(0)
	v_lshl_add_u32 v46, s9, 3, v0
	v_cmp_gt_i32_e32 vcc, s33, v46
	s_and_saveexec_b64 s[80:81], vcc
	s_cbranch_execz .LBB0_487
	s_lshl_b64 s[10:11], s[34:35], 2
	s_add_u32 s6, s6, s10
	v_and_b32_e32 v20, 63, v2
	s_addc_u32 s7, s7, s11
	v_lshlrev_b32_e32 v34, 4, v20
	global_load_dwordx4 v[2:5], v34, s[6:7]
	global_load_dwordx4 v[6:9], v34, s[6:7] offset:1024
	global_load_dwordx4 v[10:13], v34, s[6:7] offset:2048
	global_load_dwordx4 v[14:17], v34, s[6:7] offset:3072
	s_lshl_b32 s46, s8, 3
	s_add_u32 s6, s4, s90
	v_lshlrev_b32_e32 v0, 2, v20
	s_addc_u32 s7, s5, s77
	v_lshlrev_b32_e32 v18, 3, v20
	v_mov_b32_e32 v19, v1
	v_mov_b32_e32 v35, v1
	v_lshl_add_u64 v[38:39], s[64:65], 0, v[18:19]
	v_lshl_add_u64 v[18:19], s[6:7], 0, v[0:1]
	s_mov_b64 s[6:7], 0x3000
	v_lshlrev_b32_e32 v0, 16, v20
	v_lshl_add_u64 v[36:37], s[28:29], 0, v[34:35]
	v_cmp_gt_u32_e64 s[4:5], 8, v20
	v_lshl_add_u64 v[40:41], v[18:19], 0, s[6:7]
	v_lshl_add_u64 v[42:43], s[14:15], 0, v[0:1]
	v_cmp_eq_u32_e64 s[6:7], 7, v20
	v_cmp_eq_u32_e64 s[8:9], 6, v20
	v_cmp_eq_u32_e64 s[10:11], 5, v20
	v_cmp_eq_u32_e64 s[12:13], 4, v20
	v_cmp_eq_u32_e64 s[14:15], 3, v20
	v_cmp_eq_u32_e64 s[16:17], 2, v20
	v_cmp_eq_u32_e64 s[18:19], 1, v20
	v_cmp_eq_u32_e64 s[20:21], 0, v20
	s_mov_b64 s[82:83], 0
	ds_read_b128 v[84:87], v34
	ds_read_b128 v[88:91], v34 offset:1024
	ds_read_b128 v[92:95], v34 offset:2048
	ds_read_b128 v[96:99], v34 offset:3072
	ds_read_b128 v[100:103], v34 offset:4096
	ds_read_b128 v[104:107], v34 offset:5120
	ds_read_b128 v[108:111], v34 offset:6144
	ds_read_b128 v[112:115], v34 offset:7168
	ds_read_b128 v[116:119], v34 offset:8192
	ds_read_b128 v[120:123], v34 offset:9216
	ds_read_b128 v[124:127], v34 offset:10240
	ds_read_b128 v[128:131], v34 offset:11264
	ds_read_b128 v[132:135], v34 offset:12288
	ds_read_b128 v[136:139], v34 offset:13312
	ds_read_b128 v[140:143], v34 offset:14336
	ds_read_b128 v[144:147], v34 offset:15360
	ds_read_b128 v[148:151], v34 offset:16384
	ds_read_b128 v[152:155], v34 offset:17408
	ds_read_b128 v[156:159], v34 offset:18432
	ds_read_b128 v[160:163], v34 offset:19456
	ds_read_b128 v[164:167], v34 offset:20480
	ds_read_b128 v[168:171], v34 offset:21504
	ds_read_b128 v[172:175], v34 offset:22528
	ds_read_b128 v[176:179], v34 offset:23552
	ds_read_b128 v[180:183], v34 offset:24576
	ds_read_b128 v[184:187], v34 offset:25600
	ds_read_b128 v[188:191], v34 offset:26624
	ds_read_b128 v[192:195], v34 offset:27648
	ds_read_b128 v[196:199], v34 offset:28672
	ds_read_b128 v[200:203], v34 offset:29696
	ds_read_b128 v[204:207], v34 offset:30720
	ds_read_b128 v[208:211], v34 offset:31744
	s_waitcnt lgkmcnt(0)
	s_branch .LBB0_479

; DEVI unsigned cvtpk(float lo, float hi) { unsigned r; asm volatile("v_cvt_pk_bf16_f32 %0, %1, %2" : "=v"(r) : "v"(lo), "v"(hi)); return r; }
; DEVI int lbid() { int t = blockIdx.x; asm volatile("" : "+s"(t)); return t; }
; DEVI float wave_sum(float v) { v += dpp<0xB1>(v); v += dpp<0x4E>(v); v += dpp<0x124>(v); v += dpp<0x128>(v); return xrow16_sum(v); }
; DEVI void norm_phase(const float* __restrict__ x, const float* __restrict__ gain, bf16_t* __restrict__ out,
;                      const float* wf_src, const float* bf_src, float* logf, char* lds, int wv) {
;     ...
;     for (int row0 = lbid() * 8 + wave; row0 < T_TOK; row0 += 2 * nw) {
;         f32x4 v[2][4]; float ss[2];
; #pragma unroll
;         for (int q = 0; q < 2; ++q) { const int row = row0 + q * nw < T_TOK ? row0 + q * nw : row0; const float* xr = x + (size_t)row * DM;
; #pragma unroll
;             for (int j = 0; j < 4; ++j) v[q][j] = *(const f32x4*)(xr + j * 256 + lane * 4); }
; #pragma unroll
;         for (int q = 0; q < 2; ++q) { float s_ = 0.f;
; #pragma unroll
;             for (int j = 0; j < 4; ++j) s_ += v[q][j][0] * v[q][j][0] + v[q][j][1] * v[q][j][1] + v[q][j][2] * v[q][j][2] + v[q][j][3] * v[q][j][3];
;             ss[q] = wave_sum(s_); }
; #pragma unroll
;         for (int q = 0; q < 2; ++q) { const int row = row0 + q * nw; if (row >= T_TOK) break;
;             const float rstd = __builtin_amdgcn_rsqf(ss[q] * (1.f / 1024.f) + 1e-6f);
; #pragma unroll
;             for (int j = 0; j < 4; ++j) { v[q][j] = v[q][j] * rstd * g[j]; u32x2 w; w.x = cvtpk(v[q][j][0], v[q][j][1]); w.y = cvtpk(v[q][j][2], v[q][j][3]); *(u32x2*)(out + (size_t)row * DM + j * 256 + lane * 4) = w; }
.LBB0_479:
	v_ashrrev_i32_e32 v47, 31, v46
	v_lshlrev_b64 v[18:19], 12, v[46:47]
	v_lshl_add_u64 v[18:19], v[36:37], 0, v[18:19]
	global_load_dwordx4 v[48:51], v[18:19], off
	global_load_dwordx4 v[52:55], v[18:19], off offset:1024
	global_load_dwordx4 v[64:67], v[18:19], off offset:2048
	global_load_dwordx4 v[68:71], v[18:19], off offset:3072
	v_add_u32_e32 v44, s46, v46
	v_cmp_gt_i32_e64 s[22:23], s33, v44
	s_andn2_b64 vcc, exec, s[78:79]
	s_waitcnt vmcnt(0) lgkmcnt(0)
	v_mul_f32_e32 v0, v49, v49
	v_cndmask_b32_e64 v18, v46, v44, s[22:23]
	v_ashrrev_i32_e32 v19, 31, v18
	v_lshlrev_b64 v[18:19], 12, v[18:19]
	v_lshl_add_u64 v[18:19], v[36:37], 0, v[18:19]
	global_load_dwordx4 v[30:33], v[18:19], off
	global_load_dwordx4 v[26:29], v[18:19], off offset:1024
	global_load_dwordx4 v[22:25], v[18:19], off offset:2048
	s_nop 0
	global_load_dwordx4 v[18:21], v[18:19], off offset:3072
	v_mul_f32_e32 v35, v53, v53
	v_fmac_f32_e32 v0, v48, v48
	v_fmac_f32_e32 v35, v52, v52
	v_fmac_f32_e32 v0, v50, v50
	v_fmac_f32_e32 v35, v54, v54
	v_fmac_f32_e32 v0, v51, v51
	v_fmac_f32_e32 v35, v55, v55
	v_add_f32_e32 v0, v0, v35
	v_mul_f32_e32 v35, v65, v65
	v_fmac_f32_e32 v35, v64, v64
	v_fmac_f32_e32 v35, v66, v66
	v_fmac_f32_e32 v35, v67, v67
	v_add_f32_e32 v0, v0, v35
	v_mul_f32_e32 v35, v69, v69
	v_fmac_f32_e32 v35, v68, v68
	v_fmac_f32_e32 v35, v70, v70
	v_fmac_f32_e32 v35, v71, v71
	v_add_f32_e32 v0, v0, v35
	s_waitcnt vmcnt(0) lgkmcnt(0)
	v_mul_f32_e32 v45, v27, v27
	v_add_f32_dpp v0, v0, v0 quad_perm:[1,0,3,2] row_mask:0xf bank_mask:0xf bound_ctrl:1
	v_fmac_f32_e32 v45, v26, v26
	v_fmac_f32_e32 v45, v28, v28
	v_add_f32_dpp v0, v0, v0 quad_perm:[2,3,0,1] row_mask:0xf bank_mask:0xf bound_ctrl:1
	v_fmac_f32_e32 v45, v29, v29
	s_nop 0
	v_add_f32_dpp v0, v0, v0 row_ror:4 row_mask:0xf bank_mask:0xf bound_ctrl:1
	s_nop 1
	v_add_f32_dpp v0, v0, v0 row_ror:8 row_mask:0xf bank_mask:0xf bound_ctrl:1
	v_mov_b32_e32 v35, v0
	s_nop 1
	v_permlane16_swap_b32_e32 v0, v35
	v_add_f32_e32 v0, v0, v35
	v_mul_f32_e32 v35, v31, v31
	v_fmac_f32_e32 v35, v30, v30
	v_fmac_f32_e32 v35, v32, v32
	v_fmac_f32_e32 v35, v33, v33
	v_add_f32_e32 v35, v35, v45
	v_mul_f32_e32 v45, v23, v23
	v_fmac_f32_e32 v45, v22, v22
	v_mov_b32_e32 v56, v0
	v_fmac_f32_e32 v45, v24, v24
	s_nop 0
	v_permlane32_swap_b32_e32 v0, v56
	v_fmac_f32_e32 v45, v25, v25
	v_add_f32_e32 v35, v35, v45
	v_mul_f32_e32 v45, v19, v19
	v_add_f32_e32 v0, v0, v56
	v_fmac_f32_e32 v45, v18, v18
	v_fmamk_f32 v0, v0, 0x3a800000, v216
	v_fmac_f32_e32 v45, v20, v20
	v_rsq_f32_e32 v0, v0
	v_fmac_f32_e32 v45, v21, v21
	v_add_f32_e32 v35, v35, v45
	v_lshlrev_b64 v[56:57], 11, v[46:47]
	v_pk_mul_f32 v[48:49], v[48:49], v[0:1] op_sel_hi:[1,0]
	v_add_f32_dpp v35, v35, v35 quad_perm:[1,0,3,2] row_mask:0xf bank_mask:0xf bound_ctrl:1
	v_pk_mul_f32 v[50:51], v[50:51], v[0:1] op_sel_hi:[1,0]
	v_lshl_add_u64 v[72:73], v[38:39], 0, v[56:57]
	v_add_f32_dpp v35, v35, v35 quad_perm:[2,3,0,1] row_mask:0xf bank_mask:0xf bound_ctrl:1
	v_pk_mul_f32 v[60:61], v[4:5], v[50:51]
	v_pk_mul_f32 v[62:63], v[2:3], v[48:49]
	v_add_f32_dpp v35, v35, v35 row_ror:4 row_mask:0xf bank_mask:0xf bound_ctrl:1
	v_cvt_pk_bf16_f32 v48, v62, v63
	v_cvt_pk_bf16_f32 v49, v60, v61
	global_store_dwordx2 v[72:73], v[48:49], off
	v_pk_mul_f32 v[48:49], v[52:53], v[0:1] op_sel_hi:[1,0]
	v_add_f32_dpp v35, v35, v35 row_ror:8 row_mask:0xf bank_mask:0xf bound_ctrl:1
	v_pk_mul_f32 v[50:51], v[54:55], v[0:1] op_sel_hi:[1,0]
	v_mov_b32_e32 v45, v35
	v_pk_mul_f32 v[56:57], v[8:9], v[50:51]
	v_pk_mul_f32 v[58:59], v[6:7], v[48:49]
	v_permlane16_swap_b32_e32 v35, v45
	v_cvt_pk_bf16_f32 v48, v58, v59
	v_cvt_pk_bf16_f32 v49, v56, v57
	global_store_dwordx2 v[72:73], v[48:49], off offset:512
	v_pk_mul_f32 v[48:49], v[64:65], v[0:1] op_sel_hi:[1,0]
	v_pk_mul_f32 v[50:51], v[66:67], v[0:1] op_sel_hi:[1,0]
	v_add_f32_e32 v35, v35, v45
	v_pk_mul_f32 v[52:53], v[12:13], v[50:51]
	v_pk_mul_f32 v[54:55], v[10:11], v[48:49]
	v_mov_b32_e32 v45, v35
	v_cvt_pk_bf16_f32 v48, v54, v55
	v_cvt_pk_bf16_f32 v49, v52, v53
	global_store_dwordx2 v[72:73], v[48:49], off offset:1024
	v_pk_mul_f32 v[50:51], v[68:69], v[0:1] op_sel_hi:[1,0]
	v_pk_mul_f32 v[48:49], v[70:71], v[0:1] op_sel_hi:[1,0]
	v_cndmask_b32_e64 v0, 0, 1, s[78:79]
	v_permlane32_swap_b32_e32 v35, v45
	v_pk_mul_f32 v[48:49], v[16:17], v[48:49]
	v_pk_mul_f32 v[50:51], v[14:15], v[50:51]
	v_cmp_ne_u32_e64 s[24:25], 1, v0
	v_cvt_pk_bf16_f32 v64, v50, v51
	v_cvt_pk_bf16_f32 v65, v48, v49
	global_store_dwordx2 v[72:73], v[64:65], off offset:1536
	s_cbranch_vccnz .LBB0_483
; DEVI float wave_sum(float v) { v += dpp<0xB1>(v); v += dpp<0x4E>(v); v += dpp<0x124>(v); v += dpp<0x128>(v); return xrow16_sum(v); }
; DEVI void norm_phase(const float* __restrict__ x, const float* __restrict__ gain, bf16_t* __restrict__ out,
;                      const float* wf_src, const float* bf_src, float* logf, char* lds, int wv) {
;     ...
;             if (wf_src) {
;                 float z = 0.f;
; #pragma unroll
;                 for (int h = 0; h < 8; ++h) { float d = 0.f;
; #pragma unroll
;                     for (int j = 0; j < 4; ++j) { const f32x4 w = *(const f32x4*)(wf + h * 1024 + j * 256 + lane * 4); d += v[q][j][0] * w[0] + v[q][j][1] * w[1] + v[q][j][2] * w[2] + v[q][j][3] * w[3]; }
;                     d = wave_sum(d); if (lane == h) z = d; }
	v_add_u32_e32 v0, 0, v34
	v_mov_b32_e32 v64, v84
	v_mov_b32_e32 v65, v85
	v_mov_b32_e32 v66, v86
	v_mov_b32_e32 v67, v87
	v_mul_f32_e32 v47, v63, v65
	v_fmac_f32_e32 v47, v62, v64
	v_fmac_f32_e32 v47, v60, v66
	v_fmac_f32_e32 v47, v61, v67
	v_mov_b32_e32 v64, v88
	v_mov_b32_e32 v65, v89
	v_mov_b32_e32 v66, v90
	v_mov_b32_e32 v67, v91
	v_add_f32_e32 v47, 0, v47
	v_mul_f32_e32 v65, v59, v65
	v_fmac_f32_e32 v65, v58, v64
	v_fmac_f32_e32 v65, v56, v66
	v_fmac_f32_e32 v65, v57, v67
	v_add_f32_e32 v47, v47, v65
	v_mov_b32_e32 v64, v92
	v_mov_b32_e32 v65, v93
	v_mov_b32_e32 v66, v94
	v_mov_b32_e32 v67, v95
	v_mul_f32_e32 v65, v55, v65
	v_fmac_f32_e32 v65, v54, v64
	v_fmac_f32_e32 v65, v52, v66
	v_fmac_f32_e32 v65, v53, v67
	v_add_f32_e32 v47, v47, v65
	v_mov_b32_e32 v64, v96
	v_mov_b32_e32 v65, v97
	v_mov_b32_e32 v66, v98
	v_mov_b32_e32 v67, v99
	v_mul_f32_e32 v65, v51, v65
	v_fmac_f32_e32 v65, v50, v64
	v_fmac_f32_e32 v65, v48, v66
	v_fmac_f32_e32 v65, v49, v67
	v_mov_b32_e32 v66, v100
	v_mov_b32_e32 v67, v101
	v_mov_b32_e32 v68, v102
	v_mov_b32_e32 v69, v103
	v_add_f32_e32 v47, v47, v65
	v_mul_f32_e32 v65, v63, v67
	v_fmac_f32_e32 v65, v62, v66
	v_fmac_f32_e32 v65, v60, v68
	v_fmac_f32_e32 v65, v61, v69
	v_mov_b32_e32 v66, v104
	v_mov_b32_e32 v67, v105
	v_mov_b32_e32 v68, v106
	v_mov_b32_e32 v69, v107
	v_add_f32_e32 v65, 0, v65
	v_add_f32_dpp v47, v47, v47 quad_perm:[1,0,3,2] row_mask:0xf bank_mask:0xf bound_ctrl:1
	v_mul_f32_e32 v67, v59, v67
	v_fmac_f32_e32 v67, v58, v66
	v_fmac_f32_e32 v67, v56, v68
	v_fmac_f32_e32 v67, v57, v69
	v_add_f32_e32 v65, v65, v67
	v_mov_b32_e32 v66, v108
	v_mov_b32_e32 v67, v109
	v_mov_b32_e32 v68, v110
	v_mov_b32_e32 v69, v111
	v_add_f32_dpp v47, v47, v47 quad_perm:[2,3,0,1] row_mask:0xf bank_mask:0xf bound_ctrl:1
	v_mul_f32_e32 v67, v55, v67
	v_fmac_f32_e32 v67, v54, v66
	v_fmac_f32_e32 v67, v52, v68
	v_fmac_f32_e32 v67, v53, v69
	v_add_f32_e32 v65, v65, v67
	v_mov_b32_e32 v66, v112
	v_mov_b32_e32 v67, v113
	v_mov_b32_e32 v68, v114
	v_mov_b32_e32 v69, v115
	v_add_f32_dpp v47, v47, v47 row_ror:4 row_mask:0xf bank_mask:0xf bound_ctrl:1
	v_mul_f32_e32 v67, v51, v67
	v_fmac_f32_e32 v67, v50, v66
	v_fmac_f32_e32 v67, v48, v68
	v_fmac_f32_e32 v67, v49, v69
	v_mov_b32_e32 v68, v116
	v_mov_b32_e32 v69, v117
	v_mov_b32_e32 v70, v118
	v_mov_b32_e32 v71, v119
	v_add_f32_e32 v65, v65, v67
	v_add_f32_dpp v47, v47, v47 row_ror:8 row_mask:0xf bank_mask:0xf bound_ctrl:1
	v_mov_b32_e32 v64, v47
	v_add_f32_dpp v65, v65, v65 quad_perm:[1,0,3,2] row_mask:0xf bank_mask:0xf bound_ctrl:1
	v_mul_f32_e32 v67, v63, v69
	v_fmac_f32_e32 v67, v62, v68
	v_fmac_f32_e32 v67, v60, v70
	v_fmac_f32_e32 v67, v61, v71
	v_mov_b32_e32 v68, v120
	v_mov_b32_e32 v69, v121
	v_mov_b32_e32 v70, v122
	v_mov_b32_e32 v71, v123
	v_add_f32_e32 v67, 0, v67
	v_add_f32_dpp v65, v65, v65 quad_perm:[2,3,0,1] row_mask:0xf bank_mask:0xf bound_ctrl:1
	v_permlane16_swap_b32_e32 v47, v64
	v_mul_f32_e32 v69, v59, v69
	v_fmac_f32_e32 v69, v58, v68
	v_fmac_f32_e32 v69, v56, v70
	v_fmac_f32_e32 v69, v57, v71
	v_add_f32_e32 v67, v67, v69
	v_mov_b32_e32 v68, v124
	v_mov_b32_e32 v69, v125
	v_mov_b32_e32 v70, v126
	v_mov_b32_e32 v71, v127
	v_add_f32_dpp v65, v65, v65 row_ror:4 row_mask:0xf bank_mask:0xf bound_ctrl:1
	v_add_f32_e32 v47, v47, v64
	v_mov_b32_e32 v64, v47
	v_add_f32_dpp v65, v65, v65 row_ror:8 row_mask:0xf bank_mask:0xf bound_ctrl:1
	v_mul_f32_e32 v69, v55, v69
	v_fmac_f32_e32 v69, v54, v68
	v_fmac_f32_e32 v69, v52, v70
	v_fmac_f32_e32 v69, v53, v71
	v_add_f32_e32 v67, v67, v69
	v_mov_b32_e32 v68, v128
	v_mov_b32_e32 v69, v129
	v_mov_b32_e32 v70, v130
	v_mov_b32_e32 v71, v131
	v_mov_b32_e32 v66, v65
	s_nop 1
	v_permlane16_swap_b32_e32 v65, v66
	v_add_f32_e32 v65, v65, v66
	v_mul_f32_e32 v69, v51, v69
	v_fmac_f32_e32 v69, v50, v68
	v_fmac_f32_e32 v69, v48, v70
	v_fmac_f32_e32 v69, v49, v71
	v_mov_b32_e32 v70, v132
	v_mov_b32_e32 v71, v133
	v_mov_b32_e32 v72, v134
	v_mov_b32_e32 v73, v135
	v_add_f32_e32 v67, v67, v69
	v_mov_b32_e32 v66, v65
	v_permlane32_swap_b32_e32 v47, v64
	v_mul_f32_e32 v69, v63, v71
	v_fmac_f32_e32 v69, v62, v70
	v_fmac_f32_e32 v69, v60, v72
	v_fmac_f32_e32 v69, v61, v73
	v_mov_b32_e32 v70, v136
	v_mov_b32_e32 v71, v137
	v_mov_b32_e32 v72, v138
	v_mov_b32_e32 v73, v139
	v_add_f32_e32 v69, 0, v69
	v_add_f32_dpp v67, v67, v67 quad_perm:[1,0,3,2] row_mask:0xf bank_mask:0xf bound_ctrl:1
	v_permlane32_swap_b32_e32 v65, v66
	v_mul_f32_e32 v71, v59, v71
	v_fmac_f32_e32 v71, v58, v70
	v_fmac_f32_e32 v71, v56, v72
	v_fmac_f32_e32 v71, v57, v73
	v_add_f32_e32 v69, v69, v71
	v_mov_b32_e32 v70, v140
	v_mov_b32_e32 v71, v141
	v_mov_b32_e32 v72, v142
	v_mov_b32_e32 v73, v143
	v_add_f32_dpp v67, v67, v67 quad_perm:[2,3,0,1] row_mask:0xf bank_mask:0xf bound_ctrl:1
	v_mul_f32_e32 v71, v55, v71
	v_fmac_f32_e32 v71, v54, v70
	v_fmac_f32_e32 v71, v52, v72
	v_fmac_f32_e32 v71, v53, v73
	v_add_f32_e32 v69, v69, v71
	v_mov_b32_e32 v70, v144
	v_mov_b32_e32 v71, v145
	v_mov_b32_e32 v72, v146
	v_mov_b32_e32 v73, v147
	v_add_f32_dpp v67, v67, v67 row_ror:4 row_mask:0xf bank_mask:0xf bound_ctrl:1
	v_mul_f32_e32 v71, v51, v71
	v_fmac_f32_e32 v71, v50, v70
	v_fmac_f32_e32 v71, v48, v72
	v_fmac_f32_e32 v71, v49, v73
	v_mov_b32_e32 v72, v148
	v_mov_b32_e32 v73, v149
	v_mov_b32_e32 v74, v150
	v_mov_b32_e32 v75, v151
	v_add_f32_e32 v69, v69, v71
	v_add_f32_dpp v67, v67, v67 row_ror:8 row_mask:0xf bank_mask:0xf bound_ctrl:1
	v_mov_b32_e32 v68, v67
	v_add_f32_dpp v69, v69, v69 quad_perm:[1,0,3,2] row_mask:0xf bank_mask:0xf bound_ctrl:1
	v_mul_f32_e32 v71, v63, v73
	v_fmac_f32_e32 v71, v62, v72
	v_fmac_f32_e32 v71, v60, v74
	v_fmac_f32_e32 v71, v61, v75
	v_mov_b32_e32 v72, v152
; DEVI float wave_sum(float v) { v += dpp<0xB1>(v); v += dpp<0x4E>(v); v += dpp<0x124>(v); v += dpp<0x128>(v); return xrow16_sum(v); }
; DEVI void norm_phase(const float* __restrict__ x, const float* __restrict__ gain, bf16_t* __restrict__ out,
;                      const float* wf_src, const float* bf_src, float* logf, char* lds, int wv) {
;     ...
;             if (wf_src) {
;                 float z = 0.f;
; #pragma unroll
;                 for (int h = 0; h < 8; ++h) { float d = 0.f;
; #pragma unroll
;                     for (int j = 0; j < 4; ++j) { const f32x4 w = *(const f32x4*)(wf + h * 1024 + j * 256 + lane * 4); d += v[q][j][0] * w[0] + v[q][j][1] * w[1] + v[q][j][2] * w[2] + v[q][j][3] * w[3]; }
;                     d = wave_sum(d); if (lane == h) z = d; }
	v_mov_b32_e32 v73, v153
	v_mov_b32_e32 v74, v154
	v_mov_b32_e32 v75, v155
	v_add_f32_e32 v71, 0, v71
	v_add_f32_dpp v69, v69, v69 quad_perm:[2,3,0,1] row_mask:0xf bank_mask:0xf bound_ctrl:1
	v_permlane16_swap_b32_e32 v67, v68
	v_mul_f32_e32 v73, v59, v73
	v_fmac_f32_e32 v73, v58, v72
	v_fmac_f32_e32 v73, v56, v74
	v_fmac_f32_e32 v73, v57, v75
	v_add_f32_e32 v71, v71, v73
	v_mov_b32_e32 v72, v156
	v_mov_b32_e32 v73, v157
	v_mov_b32_e32 v74, v158
	v_mov_b32_e32 v75, v159
	v_add_f32_dpp v69, v69, v69 row_ror:4 row_mask:0xf bank_mask:0xf bound_ctrl:1
	v_add_f32_e32 v67, v67, v68
	v_mov_b32_e32 v68, v67
	v_add_f32_dpp v69, v69, v69 row_ror:8 row_mask:0xf bank_mask:0xf bound_ctrl:1
	v_mul_f32_e32 v73, v55, v73
	v_fmac_f32_e32 v73, v54, v72
	v_fmac_f32_e32 v73, v52, v74
	v_fmac_f32_e32 v73, v53, v75
	v_add_f32_e32 v71, v71, v73
	v_mov_b32_e32 v72, v160
	v_mov_b32_e32 v73, v161
	v_mov_b32_e32 v74, v162
	v_mov_b32_e32 v75, v163
	v_mov_b32_e32 v70, v69
	s_nop 1
	v_permlane16_swap_b32_e32 v69, v70
	v_add_f32_e32 v69, v69, v70
	v_mul_f32_e32 v73, v51, v73
	v_fmac_f32_e32 v73, v50, v72
	v_fmac_f32_e32 v73, v48, v74
	v_fmac_f32_e32 v73, v49, v75
	v_mov_b32_e32 v74, v164
	v_mov_b32_e32 v75, v165
	v_mov_b32_e32 v76, v166
	v_mov_b32_e32 v77, v167
	v_add_f32_e32 v71, v71, v73
	v_mov_b32_e32 v70, v69
	v_permlane32_swap_b32_e32 v67, v68
	v_mul_f32_e32 v73, v63, v75
	v_fmac_f32_e32 v73, v62, v74
	v_fmac_f32_e32 v73, v60, v76
	v_fmac_f32_e32 v73, v61, v77
	v_mov_b32_e32 v74, v168
	v_mov_b32_e32 v75, v169
	v_mov_b32_e32 v76, v170
	v_mov_b32_e32 v77, v171
	v_add_f32_e32 v73, 0, v73
	v_add_f32_dpp v71, v71, v71 quad_perm:[1,0,3,2] row_mask:0xf bank_mask:0xf bound_ctrl:1
	v_permlane32_swap_b32_e32 v69, v70
	v_mul_f32_e32 v75, v59, v75
	v_fmac_f32_e32 v75, v58, v74
	v_fmac_f32_e32 v75, v56, v76
	v_fmac_f32_e32 v75, v57, v77
	v_add_f32_e32 v73, v73, v75
	v_mov_b32_e32 v74, v172
	v_mov_b32_e32 v75, v173
	v_mov_b32_e32 v76, v174
	v_mov_b32_e32 v77, v175
	v_add_f32_dpp v71, v71, v71 quad_perm:[2,3,0,1] row_mask:0xf bank_mask:0xf bound_ctrl:1
	v_mul_f32_e32 v75, v55, v75
	v_fmac_f32_e32 v75, v54, v74
	v_fmac_f32_e32 v75, v52, v76
	v_fmac_f32_e32 v75, v53, v77
	v_add_f32_e32 v73, v73, v75
	v_mov_b32_e32 v74, v176
	v_mov_b32_e32 v75, v177
	v_mov_b32_e32 v76, v178
	v_mov_b32_e32 v77, v179
	v_add_f32_dpp v71, v71, v71 row_ror:4 row_mask:0xf bank_mask:0xf bound_ctrl:1
	v_mul_f32_e32 v75, v51, v75
	v_fmac_f32_e32 v75, v50, v74
	v_fmac_f32_e32 v75, v48, v76
	v_fmac_f32_e32 v75, v49, v77
	v_mov_b32_e32 v76, v180
	v_mov_b32_e32 v77, v181
	v_mov_b32_e32 v78, v182
	v_mov_b32_e32 v79, v183
	v_add_f32_e32 v73, v73, v75
	v_add_f32_dpp v71, v71, v71 row_ror:8 row_mask:0xf bank_mask:0xf bound_ctrl:1
	v_mov_b32_e32 v72, v71
	v_add_f32_dpp v73, v73, v73 quad_perm:[1,0,3,2] row_mask:0xf bank_mask:0xf bound_ctrl:1
	v_mul_f32_e32 v75, v63, v77
	v_fmac_f32_e32 v75, v62, v76
	v_fmac_f32_e32 v75, v60, v78
	v_fmac_f32_e32 v75, v61, v79
	v_mov_b32_e32 v76, v184
	v_mov_b32_e32 v77, v185
	v_mov_b32_e32 v78, v186
	v_mov_b32_e32 v79, v187
	v_add_f32_e32 v75, 0, v75
	v_add_f32_dpp v73, v73, v73 quad_perm:[2,3,0,1] row_mask:0xf bank_mask:0xf bound_ctrl:1
	v_permlane16_swap_b32_e32 v71, v72
	v_mul_f32_e32 v77, v59, v77
	v_fmac_f32_e32 v77, v58, v76
	v_fmac_f32_e32 v77, v56, v78
	v_fmac_f32_e32 v77, v57, v79
	v_add_f32_e32 v75, v75, v77
	v_mov_b32_e32 v76, v188
	v_mov_b32_e32 v77, v189
	v_mov_b32_e32 v78, v190
	v_mov_b32_e32 v79, v191
	v_add_f32_dpp v73, v73, v73 row_ror:4 row_mask:0xf bank_mask:0xf bound_ctrl:1
	v_add_f32_e32 v71, v71, v72
	v_mov_b32_e32 v72, v71
	v_add_f32_dpp v73, v73, v73 row_ror:8 row_mask:0xf bank_mask:0xf bound_ctrl:1
	v_mul_f32_e32 v77, v55, v77
	v_fmac_f32_e32 v77, v54, v76
	v_fmac_f32_e32 v77, v52, v78
	v_fmac_f32_e32 v77, v53, v79
	v_add_f32_e32 v75, v75, v77
	v_mov_b32_e32 v76, v192
	v_mov_b32_e32 v77, v193
	v_mov_b32_e32 v78, v194
	v_mov_b32_e32 v79, v195
	v_mov_b32_e32 v74, v73
	s_nop 1
	v_permlane16_swap_b32_e32 v73, v74
	v_add_f32_e32 v73, v73, v74
	v_mul_f32_e32 v77, v51, v77
	v_fmac_f32_e32 v77, v50, v76
	v_fmac_f32_e32 v77, v48, v78
	v_fmac_f32_e32 v77, v49, v79
	v_mov_b32_e32 v78, v196
	v_mov_b32_e32 v79, v197
	v_mov_b32_e32 v80, v198
	v_mov_b32_e32 v81, v199
	v_add_f32_e32 v75, v75, v77
	v_mov_b32_e32 v74, v73
	v_permlane32_swap_b32_e32 v71, v72
	v_mul_f32_e32 v63, v63, v79
	v_fmac_f32_e32 v63, v62, v78
	v_fmac_f32_e32 v63, v60, v80
	v_fmac_f32_e32 v63, v61, v81
	v_add_f32_e32 v77, 0, v63
	v_mov_b32_e32 v60, v200
	v_mov_b32_e32 v61, v201
	v_mov_b32_e32 v62, v202
	v_mov_b32_e32 v63, v203
	v_add_f32_dpp v75, v75, v75 quad_perm:[1,0,3,2] row_mask:0xf bank_mask:0xf bound_ctrl:1
	v_permlane32_swap_b32_e32 v73, v74
	s_nop 0
	v_add_f32_dpp v75, v75, v75 quad_perm:[2,3,0,1] row_mask:0xf bank_mask:0xf bound_ctrl:1
	v_mul_f32_e32 v59, v59, v61
	v_fmac_f32_e32 v59, v58, v60
	v_fmac_f32_e32 v59, v56, v62
	v_fmac_f32_e32 v59, v57, v63
	v_add_f32_e32 v60, v77, v59
	v_mov_b32_e32 v56, v204
	v_mov_b32_e32 v57, v205
	v_mov_b32_e32 v58, v206
	v_mov_b32_e32 v59, v207
	v_add_f32_dpp v75, v75, v75 row_ror:4 row_mask:0xf bank_mask:0xf bound_ctrl:1
	v_mul_f32_e32 v55, v55, v57
	v_fmac_f32_e32 v55, v54, v56
	v_fmac_f32_e32 v55, v52, v58
	v_fmac_f32_e32 v55, v53, v59
	v_add_f32_e32 v56, v60, v55
	v_mov_b32_e32 v52, v208
	v_mov_b32_e32 v53, v209
	v_mov_b32_e32 v54, v210
	v_mov_b32_e32 v55, v211
	v_add_f32_dpp v75, v75, v75 row_ror:8 row_mask:0xf bank_mask:0xf bound_ctrl:1
	v_mov_b32_e32 v76, v75
	s_nop 1
	v_permlane16_swap_b32_e32 v75, v76
	v_mul_f32_e32 v0, v51, v53
	v_fmac_f32_e32 v0, v50, v52
	v_fmac_f32_e32 v0, v48, v54
	v_fmac_f32_e32 v0, v49, v55
	v_add_f32_e32 v0, v56, v0
	v_add_f32_e32 v75, v75, v76
	v_mov_b32_e32 v76, v75
	v_add_f32_dpp v0, v0, v0 quad_perm:[1,0,3,2] row_mask:0xf bank_mask:0xf bound_ctrl:1
	s_nop 0
	v_permlane32_swap_b32_e32 v75, v76
	v_add_f32_dpp v0, v0, v0 quad_perm:[2,3,0,1] row_mask:0xf bank_mask:0xf bound_ctrl:1
	s_nop 1
	v_add_f32_dpp v0, v0, v0 row_ror:4 row_mask:0xf bank_mask:0xf bound_ctrl:1
	s_nop 1
	v_add_f32_dpp v0, v0, v0 row_ror:8 row_mask:0xf bank_mask:0xf bound_ctrl:1
	v_mov_b32_e32 v48, v0
	s_nop 1
	v_permlane16_swap_b32_e32 v0, v48
	v_add_f32_e32 v0, v0, v48
	v_mov_b32_e32 v48, v0
	s_nop 1
	v_permlane32_swap_b32_e32 v0, v48
	s_and_saveexec_b64 s[84:85], s[4:5]
	s_cbranch_execz .LBB0_482
; DEVI void norm_phase(const float* __restrict__ x, const float* __restrict__ gain, bf16_t* __restrict__ out,
;                      const float* wf_src, const float* bf_src, float* logf, char* lds, int wv) {
;     ...
;                 if (lane < 8) { z += bf_src[lane]; logf[((size_t)(row >> 14) * 8 + lane) * SEQ + (row & (SEQ - 1))] = fminf(z, 0.f) - __logf(1.f + __expf(-fabsf(z))); }
	global_load_dword v49, v[40:41], off
	v_add_f32_e32 v47, v47, v64
	v_add_f32_e32 v55, v65, v66
	v_cndmask_b32_e64 v47, 0, v47, s[20:21]
	v_add_f32_e32 v54, v67, v68
	v_cndmask_b32_e64 v47, v47, v55, s[18:19]
	v_add_f32_e32 v53, v69, v70
	v_cndmask_b32_e64 v47, v47, v54, s[16:17]
	v_add_f32_e32 v52, v71, v72
	v_cndmask_b32_e64 v47, v47, v53, s[14:15]
	v_add_f32_e32 v51, v73, v74
	v_cndmask_b32_e64 v47, v47, v52, s[12:13]
	v_add_f32_e32 v50, v75, v76
	v_cndmask_b32_e64 v47, v47, v51, s[10:11]
	v_add_f32_e32 v0, v0, v48
	v_cndmask_b32_e64 v47, v47, v50, s[8:9]
	v_cndmask_b32_e64 v0, v47, v0, s[6:7]
	s_mov_b32 s59, 0xbfb8aa3b
	v_ashrrev_i32_e32 v48, 14, v46
	v_and_b32_e32 v46, 0x3fff, v46
	s_waitcnt vmcnt(0)
	v_add_f32_e32 v50, v0, v49
	v_mul_f32_e64 v0, |v50|, s59
	v_exp_f32_e32 v51, v0
	v_ashrrev_i32_e32 v49, 31, v48
	v_lshlrev_b32_e32 v0, 2, v46
	v_lshlrev_b64 v[46:47], 19, v[48:49]
	v_add_f32_e32 v48, 1.0, v51
	s_mov_b32 s59, 0x800000
	v_cmp_gt_f32_e32 vcc, s59, v48
	s_mov_b32 s59, 0x3f317217
	v_lshl_add_u64 v[46:47], v[42:43], 0, v[46:47]
	v_cndmask_b32_e64 v49, 0, 32, vcc
	v_ldexp_f32 v48, v48, v49
	v_log_f32_e32 v48, v48
	v_min_f32_e32 v49, 0, v50
	v_mov_b32_e32 v50, 0x41b17218
	v_cndmask_b32_e32 v50, 0, v50, vcc
	v_mul_f32_e32 v51, 0x3f317217, v48
	v_fma_f32 v51, v48, s59, -v51
	v_fmac_f32_e32 v51, 0x3377d1cf, v48
	s_mov_b32 s59, 0x7f800000
	v_fmac_f32_e32 v51, 0x3f317217, v48
	v_cmp_lt_f32_e64 vcc, |v48|, s59
	v_lshl_add_u64 v[46:47], v[46:47], 0, v[0:1]
	s_nop 0
	v_cndmask_b32_e32 v48, v48, v51, vcc
	v_sub_f32_e32 v48, v48, v50
	v_sub_f32_e32 v48, v49, v48
	global_store_dword v[46:47], v48, off

; DEVI unsigned cvtpk(float lo, float hi) { unsigned r; asm volatile("v_cvt_pk_bf16_f32 %0, %1, %2" : "=v"(r) : "v"(lo), "v"(hi)); return r; }
; DEVI float wave_sum(float v) { v += dpp<0xB1>(v); v += dpp<0x4E>(v); v += dpp<0x124>(v); v += dpp<0x128>(v); return xrow16_sum(v); }
; DEVI void norm_phase(const float* __restrict__ x, const float* __restrict__ gain, bf16_t* __restrict__ out,
;                      const float* wf_src, const float* bf_src, float* logf, char* lds, int wv) {
;     ...
;         for (int q = 0; q < 2; ++q) { const int row = row0 + q * nw; if (row >= T_TOK) break;
;             const float rstd = __builtin_amdgcn_rsqf(ss[q] * (1.f / 1024.f) + 1e-6f);
; #pragma unroll
;             for (int j = 0; j < 4; ++j) { v[q][j] = v[q][j] * rstd * g[j]; u32x2 w; w.x = cvtpk(v[q][j][0], v[q][j][1]); w.y = cvtpk(v[q][j][2], v[q][j][3]); *(u32x2*)(out + (size_t)row * DM + j * 256 + lane * 4) = w; }
;             if (wf_src) {
;                 float z = 0.f;
; #pragma unroll
;                 for (int h = 0; h < 8; ++h) { float d = 0.f;
; #pragma unroll
;                     for (int j = 0; j < 4; ++j) { const f32x4 w = *(const f32x4*)(wf + h * 1024 + j * 256 + lane * 4); d += v[q][j][0] * w[0] + v[q][j][1] * w[1] + v[q][j][2] * w[2] + v[q][j][3] * w[3]; }
;                     d = wave_sum(d); if (lane == h) z = d; }
.LBB0_483:
	s_and_saveexec_b64 s[84:85], s[22:23]
	s_cbranch_execz .LBB0_478
	v_add_f32_e32 v0, v35, v45
	v_fmamk_f32 v0, v0, 0x3a800000, v216
	v_rsq_f32_e32 v0, v0
	v_ashrrev_i32_e32 v45, 31, v44
	v_lshlrev_b64 v[46:47], 11, v[44:45]
	v_lshl_add_u64 v[46:47], v[38:39], 0, v[46:47]
	v_pk_mul_f32 v[32:33], v[32:33], v[0:1] op_sel_hi:[1,0]
	v_pk_mul_f32 v[48:49], v[30:31], v[0:1] op_sel_hi:[1,0]
	v_pk_mul_f32 v[30:31], v[4:5], v[32:33]
	v_pk_mul_f32 v[32:33], v[2:3], v[48:49]
	v_pk_mul_f32 v[28:29], v[28:29], v[0:1] op_sel_hi:[1,0]
	v_cvt_pk_bf16_f32 v48, v32, v33
	v_cvt_pk_bf16_f32 v49, v30, v31
	global_store_dwordx2 v[46:47], v[48:49], off
	v_pk_mul_f32 v[48:49], v[26:27], v[0:1] op_sel_hi:[1,0]
	v_pk_mul_f32 v[26:27], v[8:9], v[28:29]
	v_pk_mul_f32 v[28:29], v[6:7], v[48:49]
	v_pk_mul_f32 v[24:25], v[24:25], v[0:1] op_sel_hi:[1,0]
	v_cvt_pk_bf16_f32 v48, v28, v29
	v_cvt_pk_bf16_f32 v49, v26, v27
	global_store_dwordx2 v[46:47], v[48:49], off offset:512
	v_pk_mul_f32 v[48:49], v[22:23], v[0:1] op_sel_hi:[1,0]
	v_pk_mul_f32 v[22:23], v[12:13], v[24:25]
	v_pk_mul_f32 v[24:25], v[10:11], v[48:49]
	v_pk_mul_f32 v[20:21], v[20:21], v[0:1] op_sel_hi:[1,0]
	v_cvt_pk_bf16_f32 v48, v24, v25
	v_cvt_pk_bf16_f32 v49, v22, v23
	global_store_dwordx2 v[46:47], v[48:49], off offset:1024
	v_pk_mul_f32 v[48:49], v[18:19], v[0:1] op_sel_hi:[1,0]
	v_pk_mul_f32 v[18:19], v[16:17], v[20:21]
	v_pk_mul_f32 v[20:21], v[14:15], v[48:49]
	s_and_b64 vcc, exec, s[24:25]
	v_cvt_pk_bf16_f32 v48, v20, v21
	v_cvt_pk_bf16_f32 v49, v18, v19
	global_store_dwordx2 v[46:47], v[48:49], off offset:1536
	s_cbranch_vccnz .LBB0_478
	v_add_u32_e32 v0, 0, v34
	v_mov_b32_e32 v46, v84
	v_mov_b32_e32 v47, v85
	v_mov_b32_e32 v48, v86
	v_mov_b32_e32 v49, v87
	v_mul_f32_e32 v35, v33, v47
	v_fmac_f32_e32 v35, v32, v46
	v_fmac_f32_e32 v35, v30, v48
	v_fmac_f32_e32 v35, v31, v49
	v_mov_b32_e32 v46, v88
	v_mov_b32_e32 v47, v89
	v_mov_b32_e32 v48, v90
	v_mov_b32_e32 v49, v91
	v_add_f32_e32 v35, 0, v35
	v_mul_f32_e32 v45, v29, v47
	v_fmac_f32_e32 v45, v28, v46
	v_fmac_f32_e32 v45, v26, v48
	v_fmac_f32_e32 v45, v27, v49
	v_mov_b32_e32 v46, v92
	v_mov_b32_e32 v47, v93
	v_mov_b32_e32 v48, v94
	v_mov_b32_e32 v49, v95
	v_add_f32_e32 v35, v35, v45
	v_mul_f32_e32 v45, v25, v47
	v_fmac_f32_e32 v45, v24, v46
	v_fmac_f32_e32 v45, v22, v48
	v_fmac_f32_e32 v45, v23, v49
	v_mov_b32_e32 v46, v96
	v_mov_b32_e32 v47, v97
	v_mov_b32_e32 v48, v98
	v_mov_b32_e32 v49, v99
	v_add_f32_e32 v35, v35, v45
	v_mul_f32_e32 v45, v21, v47
	v_fmac_f32_e32 v45, v20, v46
	v_fmac_f32_e32 v45, v18, v48
	v_fmac_f32_e32 v45, v19, v49
	v_mov_b32_e32 v46, v100
	v_mov_b32_e32 v47, v101
	v_mov_b32_e32 v48, v102
	v_mov_b32_e32 v49, v103
	v_add_f32_e32 v35, v35, v45
	v_mul_f32_e32 v47, v33, v47
	v_fmac_f32_e32 v47, v32, v46
	v_fmac_f32_e32 v47, v30, v48
	v_fmac_f32_e32 v47, v31, v49
	v_add_f32_e32 v50, 0, v47
	v_mov_b32_e32 v46, v104
	v_mov_b32_e32 v47, v105
	v_mov_b32_e32 v48, v106
	v_mov_b32_e32 v49, v107
	v_add_f32_dpp v35, v35, v35 quad_perm:[1,0,3,2] row_mask:0xf bank_mask:0xf bound_ctrl:1
	v_mul_f32_e32 v47, v29, v47
	v_fmac_f32_e32 v47, v28, v46
	v_fmac_f32_e32 v47, v26, v48
	v_fmac_f32_e32 v47, v27, v49
	v_add_f32_e32 v50, v50, v47
	v_mov_b32_e32 v46, v108
	v_mov_b32_e32 v47, v109
	v_mov_b32_e32 v48, v110
	v_mov_b32_e32 v49, v111
	v_add_f32_dpp v35, v35, v35 quad_perm:[2,3,0,1] row_mask:0xf bank_mask:0xf bound_ctrl:1
	v_mul_f32_e32 v47, v25, v47
	v_fmac_f32_e32 v47, v24, v46
	v_fmac_f32_e32 v47, v22, v48
	v_fmac_f32_e32 v47, v23, v49
	v_add_f32_e32 v50, v50, v47
	v_mov_b32_e32 v46, v112
	v_mov_b32_e32 v47, v113
	v_mov_b32_e32 v48, v114
	v_mov_b32_e32 v49, v115
	v_add_f32_dpp v35, v35, v35 row_ror:4 row_mask:0xf bank_mask:0xf bound_ctrl:1
	v_mul_f32_e32 v47, v21, v47
	v_fmac_f32_e32 v47, v20, v46
	v_fmac_f32_e32 v47, v18, v48
	v_fmac_f32_e32 v47, v19, v49
	v_add_f32_e32 v46, v50, v47
	v_mov_b32_e32 v48, v116
	v_mov_b32_e32 v49, v117
	v_mov_b32_e32 v50, v118
	v_mov_b32_e32 v51, v119
	v_add_f32_dpp v35, v35, v35 row_ror:8 row_mask:0xf bank_mask:0xf bound_ctrl:1
	v_add_f32_dpp v46, v46, v46 quad_perm:[1,0,3,2] row_mask:0xf bank_mask:0xf bound_ctrl:1
	v_mov_b32_e32 v45, v35
	s_nop 1
	v_permlane16_swap_b32_e32 v35, v45
	v_mul_f32_e32 v49, v33, v49
	v_fmac_f32_e32 v49, v32, v48
	v_fmac_f32_e32 v49, v30, v50
	v_fmac_f32_e32 v49, v31, v51
	v_add_f32_e32 v52, 0, v49
	v_mov_b32_e32 v48, v120
	v_mov_b32_e32 v49, v121
	v_mov_b32_e32 v50, v122
	v_mov_b32_e32 v51, v123
	v_add_f32_dpp v46, v46, v46 quad_perm:[2,3,0,1] row_mask:0xf bank_mask:0xf bound_ctrl:1
	v_add_f32_e32 v35, v35, v45
	v_mov_b32_e32 v45, v35
	v_add_f32_dpp v46, v46, v46 row_ror:4 row_mask:0xf bank_mask:0xf bound_ctrl:1
	v_mul_f32_e32 v49, v29, v49
	v_fmac_f32_e32 v49, v28, v48
	v_fmac_f32_e32 v49, v26, v50
	v_fmac_f32_e32 v49, v27, v51
	v_add_f32_e32 v52, v52, v49
	v_mov_b32_e32 v48, v124
	v_mov_b32_e32 v49, v125
	v_mov_b32_e32 v50, v126
	v_mov_b32_e32 v51, v127
	v_add_f32_dpp v46, v46, v46 row_ror:8 row_mask:0xf bank_mask:0xf bound_ctrl:1
	v_mov_b32_e32 v47, v46
	s_nop 1
	v_permlane16_swap_b32_e32 v46, v47
	v_mul_f32_e32 v49, v25, v49
	v_fmac_f32_e32 v49, v24, v48
	v_fmac_f32_e32 v49, v22, v50
	v_fmac_f32_e32 v49, v23, v51
	v_add_f32_e32 v52, v52, v49
	v_mov_b32_e32 v48, v128
	v_mov_b32_e32 v49, v129
	v_mov_b32_e32 v50, v130
	v_mov_b32_e32 v51, v131
	v_add_f32_e32 v46, v46, v47
	v_mov_b32_e32 v47, v46
	v_permlane32_swap_b32_e32 v35, v45
	v_mul_f32_e32 v49, v21, v49
	v_fmac_f32_e32 v49, v20, v48
	v_fmac_f32_e32 v49, v18, v50
	v_fmac_f32_e32 v49, v19, v51
	v_add_f32_e32 v48, v52, v49
	v_mov_b32_e32 v50, v132
	v_mov_b32_e32 v51, v133
	v_mov_b32_e32 v52, v134
	v_mov_b32_e32 v53, v135
; DEVI float wave_sum(float v) { v += dpp<0xB1>(v); v += dpp<0x4E>(v); v += dpp<0x124>(v); v += dpp<0x128>(v); return xrow16_sum(v); }
; DEVI void norm_phase(const float* __restrict__ x, const float* __restrict__ gain, bf16_t* __restrict__ out,
;                      const float* wf_src, const float* bf_src, float* logf, char* lds, int wv) {
;     ...
;             if (wf_src) {
;                 float z = 0.f;
; #pragma unroll
;                 for (int h = 0; h < 8; ++h) { float d = 0.f;
; #pragma unroll
;                     for (int j = 0; j < 4; ++j) { const f32x4 w = *(const f32x4*)(wf + h * 1024 + j * 256 + lane * 4); d += v[q][j][0] * w[0] + v[q][j][1] * w[1] + v[q][j][2] * w[2] + v[q][j][3] * w[3]; }
;                     d = wave_sum(d); if (lane == h) z = d; }
	v_permlane32_swap_b32_e32 v46, v47
	v_add_f32_dpp v48, v48, v48 quad_perm:[1,0,3,2] row_mask:0xf bank_mask:0xf bound_ctrl:1
	v_mul_f32_e32 v51, v33, v51
	v_fmac_f32_e32 v51, v32, v50
	v_fmac_f32_e32 v51, v30, v52
	v_fmac_f32_e32 v51, v31, v53
	v_add_f32_e32 v54, 0, v51
	v_mov_b32_e32 v50, v136
	v_mov_b32_e32 v51, v137
	v_mov_b32_e32 v52, v138
	v_mov_b32_e32 v53, v139
	v_add_f32_dpp v48, v48, v48 quad_perm:[2,3,0,1] row_mask:0xf bank_mask:0xf bound_ctrl:1
	v_mul_f32_e32 v51, v29, v51
	v_fmac_f32_e32 v51, v28, v50
	v_fmac_f32_e32 v51, v26, v52
	v_fmac_f32_e32 v51, v27, v53
	v_add_f32_e32 v54, v54, v51
	v_mov_b32_e32 v50, v140
	v_mov_b32_e32 v51, v141
	v_mov_b32_e32 v52, v142
	v_mov_b32_e32 v53, v143
	v_add_f32_dpp v48, v48, v48 row_ror:4 row_mask:0xf bank_mask:0xf bound_ctrl:1
	v_mul_f32_e32 v51, v25, v51
	v_fmac_f32_e32 v51, v24, v50
	v_fmac_f32_e32 v51, v22, v52
	v_fmac_f32_e32 v51, v23, v53
	v_add_f32_e32 v54, v54, v51
	v_mov_b32_e32 v50, v144
	v_mov_b32_e32 v51, v145
	v_mov_b32_e32 v52, v146
	v_mov_b32_e32 v53, v147
	v_add_f32_dpp v48, v48, v48 row_ror:8 row_mask:0xf bank_mask:0xf bound_ctrl:1
	v_mov_b32_e32 v49, v48
	s_nop 1
	v_permlane16_swap_b32_e32 v48, v49
	v_mul_f32_e32 v51, v21, v51
	v_fmac_f32_e32 v51, v20, v50
	v_fmac_f32_e32 v51, v18, v52
	v_fmac_f32_e32 v51, v19, v53
	v_add_f32_e32 v50, v54, v51
	v_mov_b32_e32 v52, v148
	v_mov_b32_e32 v53, v149
	v_mov_b32_e32 v54, v150
	v_mov_b32_e32 v55, v151
	v_add_f32_e32 v48, v48, v49
	v_add_f32_dpp v50, v50, v50 quad_perm:[1,0,3,2] row_mask:0xf bank_mask:0xf bound_ctrl:1
	v_mov_b32_e32 v49, v48
	s_nop 1
	v_permlane32_swap_b32_e32 v48, v49
	v_mul_f32_e32 v53, v33, v53
	v_fmac_f32_e32 v53, v32, v52
	v_fmac_f32_e32 v53, v30, v54
	v_fmac_f32_e32 v53, v31, v55
	v_add_f32_e32 v56, 0, v53
	v_mov_b32_e32 v52, v152
	v_mov_b32_e32 v53, v153
	v_mov_b32_e32 v54, v154
	v_mov_b32_e32 v55, v155
	v_add_f32_dpp v50, v50, v50 quad_perm:[2,3,0,1] row_mask:0xf bank_mask:0xf bound_ctrl:1
	v_mul_f32_e32 v53, v29, v53
	v_fmac_f32_e32 v53, v28, v52
	v_fmac_f32_e32 v53, v26, v54
	v_fmac_f32_e32 v53, v27, v55
	v_add_f32_e32 v56, v56, v53
	v_mov_b32_e32 v52, v156
	v_mov_b32_e32 v53, v157
	v_mov_b32_e32 v54, v158
	v_mov_b32_e32 v55, v159
	v_add_f32_dpp v50, v50, v50 row_ror:4 row_mask:0xf bank_mask:0xf bound_ctrl:1
	v_mul_f32_e32 v53, v25, v53
	v_fmac_f32_e32 v53, v24, v52
	v_fmac_f32_e32 v53, v22, v54
	v_fmac_f32_e32 v53, v23, v55
	v_add_f32_e32 v56, v56, v53
	v_mov_b32_e32 v52, v160
	v_mov_b32_e32 v53, v161
	v_mov_b32_e32 v54, v162
	v_mov_b32_e32 v55, v163
	v_add_f32_dpp v50, v50, v50 row_ror:8 row_mask:0xf bank_mask:0xf bound_ctrl:1
	v_mov_b32_e32 v51, v50
	s_nop 1
	v_permlane16_swap_b32_e32 v50, v51
	v_mul_f32_e32 v53, v21, v53
	v_fmac_f32_e32 v53, v20, v52
	v_fmac_f32_e32 v53, v18, v54
	v_fmac_f32_e32 v53, v19, v55
	v_add_f32_e32 v52, v56, v53
	v_mov_b32_e32 v54, v164
	v_mov_b32_e32 v55, v165
	v_mov_b32_e32 v56, v166
	v_mov_b32_e32 v57, v167
	v_add_f32_e32 v50, v50, v51
	v_add_f32_dpp v52, v52, v52 quad_perm:[1,0,3,2] row_mask:0xf bank_mask:0xf bound_ctrl:1
	v_mov_b32_e32 v51, v50
	s_nop 1
	v_permlane32_swap_b32_e32 v50, v51
	v_mul_f32_e32 v55, v33, v55
	v_fmac_f32_e32 v55, v32, v54
	v_fmac_f32_e32 v55, v30, v56
	v_fmac_f32_e32 v55, v31, v57
	v_add_f32_e32 v58, 0, v55
	v_mov_b32_e32 v54, v168
	v_mov_b32_e32 v55, v169
	v_mov_b32_e32 v56, v170
	v_mov_b32_e32 v57, v171
	v_add_f32_dpp v52, v52, v52 quad_perm:[2,3,0,1] row_mask:0xf bank_mask:0xf bound_ctrl:1
	v_mul_f32_e32 v55, v29, v55
	v_fmac_f32_e32 v55, v28, v54
	v_fmac_f32_e32 v55, v26, v56
	v_fmac_f32_e32 v55, v27, v57
	v_add_f32_e32 v58, v58, v55
	v_mov_b32_e32 v54, v172
	v_mov_b32_e32 v55, v173
	v_mov_b32_e32 v56, v174
	v_mov_b32_e32 v57, v175
	v_add_f32_dpp v52, v52, v52 row_ror:4 row_mask:0xf bank_mask:0xf bound_ctrl:1
	v_mul_f32_e32 v55, v25, v55
	v_fmac_f32_e32 v55, v24, v54
	v_fmac_f32_e32 v55, v22, v56
	v_fmac_f32_e32 v55, v23, v57
	v_add_f32_e32 v58, v58, v55
	v_mov_b32_e32 v54, v176
	v_mov_b32_e32 v55, v177
	v_mov_b32_e32 v56, v178
	v_mov_b32_e32 v57, v179
	v_add_f32_dpp v52, v52, v52 row_ror:8 row_mask:0xf bank_mask:0xf bound_ctrl:1
	v_mov_b32_e32 v53, v52
	s_nop 1
	v_permlane16_swap_b32_e32 v52, v53
	v_mul_f32_e32 v55, v21, v55
	v_fmac_f32_e32 v55, v20, v54
	v_fmac_f32_e32 v55, v18, v56
	v_fmac_f32_e32 v55, v19, v57
	v_add_f32_e32 v54, v58, v55
	v_mov_b32_e32 v56, v180
	v_mov_b32_e32 v57, v181
	v_mov_b32_e32 v58, v182
	v_mov_b32_e32 v59, v183
	v_add_f32_e32 v52, v52, v53
	v_add_f32_dpp v54, v54, v54 quad_perm:[1,0,3,2] row_mask:0xf bank_mask:0xf bound_ctrl:1
	v_mov_b32_e32 v53, v52
	s_nop 1
	v_permlane32_swap_b32_e32 v52, v53
	v_mul_f32_e32 v57, v33, v57
	v_fmac_f32_e32 v57, v32, v56
	v_fmac_f32_e32 v57, v30, v58
	v_fmac_f32_e32 v57, v31, v59
	v_add_f32_e32 v60, 0, v57
	v_mov_b32_e32 v56, v184
	v_mov_b32_e32 v57, v185
; DEVI float wave_sum(float v) { v += dpp<0xB1>(v); v += dpp<0x4E>(v); v += dpp<0x124>(v); v += dpp<0x128>(v); return xrow16_sum(v); }
; DEVI void norm_phase(const float* __restrict__ x, const float* __restrict__ gain, bf16_t* __restrict__ out,
;                      const float* wf_src, const float* bf_src, float* logf, char* lds, int wv) {
;     ...
;             if (wf_src) {
;                 float z = 0.f;
; #pragma unroll
;                 for (int h = 0; h < 8; ++h) { float d = 0.f;
; #pragma unroll
;                     for (int j = 0; j < 4; ++j) { const f32x4 w = *(const f32x4*)(wf + h * 1024 + j * 256 + lane * 4); d += v[q][j][0] * w[0] + v[q][j][1] * w[1] + v[q][j][2] * w[2] + v[q][j][3] * w[3]; }
;                     d = wave_sum(d); if (lane == h) z = d; }
;                 if (lane < 8) { z += bf_src[lane]; logf[((size_t)(row >> 14) * 8 + lane) * SEQ + (row & (SEQ - 1))] = fminf(z, 0.f) - __logf(1.f + __expf(-fabsf(z))); }
	v_mov_b32_e32 v58, v186
	v_mov_b32_e32 v59, v187
	v_add_f32_dpp v54, v54, v54 quad_perm:[2,3,0,1] row_mask:0xf bank_mask:0xf bound_ctrl:1
	v_mul_f32_e32 v57, v29, v57
	v_fmac_f32_e32 v57, v28, v56
	v_fmac_f32_e32 v57, v26, v58
	v_fmac_f32_e32 v57, v27, v59
	v_add_f32_e32 v60, v60, v57
	v_mov_b32_e32 v56, v188
	v_mov_b32_e32 v57, v189
	v_mov_b32_e32 v58, v190
	v_mov_b32_e32 v59, v191
	v_add_f32_dpp v54, v54, v54 row_ror:4 row_mask:0xf bank_mask:0xf bound_ctrl:1
	v_mul_f32_e32 v57, v25, v57
	v_fmac_f32_e32 v57, v24, v56
	v_fmac_f32_e32 v57, v22, v58
	v_fmac_f32_e32 v57, v23, v59
	v_add_f32_e32 v60, v60, v57
	v_mov_b32_e32 v56, v192
	v_mov_b32_e32 v57, v193
	v_mov_b32_e32 v58, v194
	v_mov_b32_e32 v59, v195
	v_add_f32_dpp v54, v54, v54 row_ror:8 row_mask:0xf bank_mask:0xf bound_ctrl:1
	v_mov_b32_e32 v55, v54
	s_nop 1
	v_permlane16_swap_b32_e32 v54, v55
	v_mul_f32_e32 v57, v21, v57
	v_fmac_f32_e32 v57, v20, v56
	v_fmac_f32_e32 v57, v18, v58
	v_fmac_f32_e32 v57, v19, v59
	v_add_f32_e32 v56, v60, v57
	v_mov_b32_e32 v58, v196
	v_mov_b32_e32 v59, v197
	v_mov_b32_e32 v60, v198
	v_mov_b32_e32 v61, v199
	v_add_f32_e32 v54, v54, v55
	v_add_f32_dpp v56, v56, v56 quad_perm:[1,0,3,2] row_mask:0xf bank_mask:0xf bound_ctrl:1
	v_mov_b32_e32 v55, v54
	s_nop 1
	v_permlane32_swap_b32_e32 v54, v55
	v_mul_f32_e32 v33, v33, v59
	v_fmac_f32_e32 v33, v32, v58
	v_fmac_f32_e32 v33, v30, v60
	v_fmac_f32_e32 v33, v31, v61
	v_add_f32_e32 v58, 0, v33
	v_mov_b32_e32 v30, v200
	v_mov_b32_e32 v31, v201
	v_mov_b32_e32 v32, v202
	v_mov_b32_e32 v33, v203
	v_add_f32_dpp v56, v56, v56 quad_perm:[2,3,0,1] row_mask:0xf bank_mask:0xf bound_ctrl:1
	v_mul_f32_e32 v29, v29, v31
	v_fmac_f32_e32 v29, v28, v30
	v_fmac_f32_e32 v29, v26, v32
	v_fmac_f32_e32 v29, v27, v33
	v_add_f32_e32 v30, v58, v29
	v_mov_b32_e32 v26, v204
	v_mov_b32_e32 v27, v205
	v_mov_b32_e32 v28, v206
	v_mov_b32_e32 v29, v207
	v_add_f32_dpp v56, v56, v56 row_ror:4 row_mask:0xf bank_mask:0xf bound_ctrl:1
	v_mul_f32_e32 v25, v25, v27
	v_fmac_f32_e32 v25, v24, v26
	v_fmac_f32_e32 v25, v22, v28
	v_fmac_f32_e32 v25, v23, v29
	v_add_f32_e32 v26, v30, v25
	v_mov_b32_e32 v22, v208
	v_mov_b32_e32 v23, v209
	v_mov_b32_e32 v24, v210
	v_mov_b32_e32 v25, v211
	v_add_f32_dpp v56, v56, v56 row_ror:8 row_mask:0xf bank_mask:0xf bound_ctrl:1
	v_mov_b32_e32 v57, v56
	s_nop 1
	v_permlane16_swap_b32_e32 v56, v57
	v_mul_f32_e32 v0, v21, v23
	v_fmac_f32_e32 v0, v20, v22
	v_fmac_f32_e32 v0, v18, v24
	v_fmac_f32_e32 v0, v19, v25
	v_add_f32_e32 v0, v26, v0
	v_add_f32_e32 v56, v56, v57
	v_mov_b32_e32 v57, v56
	v_add_f32_dpp v0, v0, v0 quad_perm:[1,0,3,2] row_mask:0xf bank_mask:0xf bound_ctrl:1
	s_nop 0
	v_permlane32_swap_b32_e32 v56, v57
	v_add_f32_dpp v0, v0, v0 quad_perm:[2,3,0,1] row_mask:0xf bank_mask:0xf bound_ctrl:1
	s_nop 1
	v_add_f32_dpp v0, v0, v0 row_ror:4 row_mask:0xf bank_mask:0xf bound_ctrl:1
	s_nop 1
	v_add_f32_dpp v0, v0, v0 row_ror:8 row_mask:0xf bank_mask:0xf bound_ctrl:1
	v_mov_b32_e32 v18, v0
	s_nop 1
	v_permlane16_swap_b32_e32 v0, v18
	v_add_f32_e32 v0, v0, v18
	v_mov_b32_e32 v18, v0
	s_nop 1
	v_permlane32_swap_b32_e32 v0, v18
	s_and_b64 exec, exec, s[4:5]
	s_cbranch_execz .LBB0_478
	global_load_dword v19, v[40:41], off
	v_add_f32_e32 v26, v35, v45
	v_add_f32_e32 v25, v46, v47
	v_cndmask_b32_e64 v26, 0, v26, s[20:21]
	v_add_f32_e32 v24, v48, v49
	v_cndmask_b32_e64 v25, v26, v25, s[18:19]
	v_add_f32_e32 v23, v50, v51
	v_cndmask_b32_e64 v24, v25, v24, s[16:17]
	v_add_f32_e32 v22, v52, v53
	v_cndmask_b32_e64 v23, v24, v23, s[14:15]
	v_add_f32_e32 v21, v54, v55
	v_cndmask_b32_e64 v22, v23, v22, s[12:13]
	v_add_f32_e32 v20, v56, v57
	v_cndmask_b32_e64 v21, v22, v21, s[10:11]
	v_add_f32_e32 v0, v0, v18
	v_cndmask_b32_e64 v20, v21, v20, s[8:9]
	v_cndmask_b32_e64 v0, v20, v0, s[6:7]
	s_mov_b32 s22, 0xbfb8aa3b
	v_ashrrev_i32_e32 v18, 14, v44
	v_and_b32_e32 v27, 0x3fff, v44
	s_waitcnt vmcnt(0)
	v_add_f32_e32 v20, v0, v19
	v_mul_f32_e64 v0, |v20|, s22
	v_exp_f32_e32 v21, v0
	s_mov_b32 s22, 0x800000
	v_ashrrev_i32_e32 v19, 31, v18
	v_lshlrev_b64 v[18:19], 19, v[18:19]
	v_add_f32_e32 v21, 1.0, v21
	v_cmp_gt_f32_e32 vcc, s22, v21
	s_mov_b32 s22, 0x3f317217
	v_lshlrev_b32_e32 v0, 2, v27
	v_cndmask_b32_e64 v22, 0, 32, vcc
	v_ldexp_f32 v21, v21, v22
	v_log_f32_e32 v21, v21
	v_mov_b32_e32 v22, 0x41b17218
	v_cndmask_b32_e32 v22, 0, v22, vcc
	v_lshl_add_u64 v[18:19], v[42:43], 0, v[18:19]
	v_mul_f32_e32 v23, 0x3f317217, v21
	v_fma_f32 v23, v21, s22, -v23
	v_fmac_f32_e32 v23, 0x3377d1cf, v21
	s_mov_b32 s22, 0x7f800000
	v_fmac_f32_e32 v23, 0x3f317217, v21
	v_cmp_lt_f32_e64 vcc, |v21|, s22
	v_min_f32_e32 v20, 0, v20
	v_lshl_add_u64 v[18:19], v[18:19], 0, v[0:1]
	v_cndmask_b32_e32 v21, v21, v23, vcc
	v_sub_f32_e32 v21, v21, v22
	v_sub_f32_e32 v20, v20, v21
	global_store_dword v[18:19], v20, off
	s_branch .LBB0_478
